# K56 + attention P->bf16 by v_cvt_pk_bf16_f32 (instruction selection, 48 -> 8 VALU per key tile) stacked
# baseline (speedup 1.0000x reference)
.Lmy_kpf_b:
	s_nop 11
	v_mov_b32_e32 v96, v42
	v_mov_b32_e32 v116, v43
	v_mov_b32_e32 v42, v34
	v_mov_b32_e32 v43, v36
	v_pk_fma_f32 v[42:43], v[42:43], s[16:17], v[156:157] op_sel_hi:[1,0,1] neg_lo:[0,0,1] neg_hi:[0,0,1]
	v_mov_b32_e32 v36, v35
	v_cndmask_b32_e32 v0, v126, v43, vcc
	v_cmp_gt_u32_e32 vcc, s21, v176
	v_mov_b32_e32 v110, v46
	v_pk_fma_f32 v[36:37], v[36:37], s[16:17], v[158:159] op_sel_hi:[1,0,1] neg_lo:[0,0,1] neg_hi:[0,0,1]
	v_cndmask_b32_e32 v46, v126, v42, vcc
	v_cmp_gt_u32_e32 vcc, s21, v177
	v_mov_b32_e32 v108, v47
	v_mov_b32_e32 v34, v38
	v_mov_b32_e32 v35, v40
	v_mov_b32_e32 v40, v39
	v_pk_mul_f32 v[38:39], v[96:97], v[90:91]
	v_cvt_f32_i32_e32 v91, v163
	v_cndmask_b32_e32 v47, v126, v37, vcc
	v_cmp_gt_u32_e32 vcc, s21, v178
	v_mov_b32_e32 v106, v48
	v_pk_fma_f32 v[34:35], v[34:35], s[16:17], v[160:161] op_sel_hi:[1,0,1] neg_lo:[0,0,1] neg_hi:[0,0,1]
	v_cndmask_b32_e32 v48, v126, v36, vcc
	v_cmp_gt_u32_e32 vcc, s21, v179
	v_mov_b32_e32 v104, v49
	v_mov_b32_e32 v154, v44
	v_cndmask_b32_e32 v49, v126, v35, vcc
	v_cmp_gt_u32_e32 vcc, s21, v180
	v_mov_b32_e32 v112, v45
	v_mov_b32_e32 v44, v38
	v_cndmask_b32_e32 v96, v126, v34, vcc
	v_max3_f32 v34, v46, s22, v48
	v_max3_f32 v114, v34, v0, v47
	v_pk_mul_f32 v[34:35], v[154:155], v[90:91]
	v_cvt_f32_i32_e32 v91, v170
	v_mov_b32_e32 v45, v34
	v_mov_b32_e32 v34, v39
	v_pk_add_f32 v[34:35], v[44:45], v[34:35] neg_lo:[0,1] neg_hi:[0,1]
	v_pk_mul_f32 v[36:37], v[116:117], v[90:91]
	v_cvt_f32_i32_e32 v91, v169
	v_cmp_gt_u32_e32 vcc, s21, v163
	v_mov_b32_e32 v38, v36
	s_nop 0
	v_cndmask_b32_e32 v44, v126, v35, vcc
	v_cmp_gt_u32_e32 vcc, s21, v168
	s_nop 1
	v_cndmask_b32_e32 v45, v126, v34, vcc
	v_pk_mul_f32 v[34:35], v[112:113], v[90:91]
	v_cvt_f32_i32_e32 v91, v172
	v_mov_b32_e32 v39, v34
	v_mov_b32_e32 v34, v37
	v_pk_add_f32 v[34:35], v[38:39], v[34:35] neg_lo:[0,1] neg_hi:[0,1]
	v_pk_mul_f32 v[36:37], v[110:111], v[90:91]
	v_cvt_f32_i32_e32 v91, v174
	v_cmp_gt_u32_e32 vcc, s21, v169
	v_pk_mul_f32 v[38:39], v[108:109], v[90:91]
	v_cvt_f32_i32_e32 v91, v171
	v_cndmask_b32_e32 v110, v126, v35, vcc
	v_cmp_gt_u32_e32 vcc, s21, v170
	v_pk_mul_f32 v[42:43], v[106:107], v[90:91]
	v_cvt_f32_i32_e32 v91, v173
	v_cndmask_b32_e32 v108, v126, v34, vcc
	v_mov_b32_e32 v34, v36
	v_mov_b32_e32 v35, v42
	v_mov_b32_e32 v42, v37
	v_pk_add_f32 v[34:35], v[34:35], v[42:43] neg_lo:[0,1] neg_hi:[0,1]
	v_cmp_gt_u32_e32 vcc, s21, v171
	v_mov_b32_e32 v36, v38
	s_nop 0
	v_cndmask_b32_e32 v42, v126, v35, vcc
	v_cmp_gt_u32_e32 vcc, s21, v172
	s_nop 1
	v_cndmask_b32_e32 v43, v126, v34, vcc
	v_pk_mul_f32 v[34:35], v[104:105], v[90:91]
	v_cmp_gt_u32_e32 vcc, s21, v173
	v_mov_b32_e32 v37, v34
	v_mov_b32_e32 v34, v39
	v_pk_add_f32 v[34:35], v[36:37], v[34:35] neg_lo:[0,1] neg_hi:[0,1]
	s_nop 0
	v_cndmask_b32_e32 v91, v126, v35, vcc
	v_cmp_gt_u32_e32 vcc, s21, v174
	s_nop 1
	v_cndmask_b32_e32 v104, v126, v34, vcc
	v_pk_mul_f32 v[34:35], v[102:103], v[164:165]
	v_cmp_gt_u32_e32 vcc, s21, v182
	v_pk_fma_f32 v[34:35], v[40:41], s[16:17], v[34:35] op_sel_hi:[1,0,1] neg_lo:[0,0,1] neg_hi:[0,0,1]
	s_nop 0
	v_cndmask_b32_e32 v105, v126, v35, vcc
	v_cmp_gt_u32_e32 vcc, s21, v183
	s_nop 1
	v_cndmask_b32_e32 v106, v126, v34, vcc
	v_max3_f32 v34, v114, v96, v106
	v_max3_f32 v34, v34, v49, v105
	v_max3_f32 v34, v34, v45, v108
	v_max3_f32 v34, v34, v44, v110
	v_max3_f32 v34, v34, v43, v104
	v_max3_f32 v34, v34, v42, v91
	ds_bpermute_b32 v35, v184, v34
	s_waitcnt lgkmcnt(0)
	v_max3_f32 v107, v133, v34, v35
	v_sub_f32_e32 v34, v46, v107
	v_sub_f32_e32 v111, v133, v107
	v_mov_b32_e32 v133, v107
	v_exp_f32_e32 v109, v34
	ds_read_b64_tr_b16 v[38:39], v124
	ds_read_b64_tr_b16 v[40:41], v124 offset:1024
	ds_read_b64_tr_b16 v[36:37], v124 offset:1088
	ds_read_b64_tr_b16 v[34:35], v124 offset:64
	v_sub_f32_e32 v112, v48, v107
	s_nop 1
	v_sub_f32_e32 v113, v0, v107
	v_exp_f32_e32 v112, v112
	s_nop 0
	v_exp_f32_e32 v113, v113
	v_cmp_lt_f32_e32 vcc, s23, v0
	v_sub_f32_e32 v0, v47, v107
	v_cmp_lt_f32_e64 s[2:3], s23, v46
	v_cndmask_b32_e32 v113, 0, v113, vcc
	s_nop 0
	v_cndmask_b32_e64 v46, 0, v109, s[2:3]
	s_nop 0
	v_exp_f32_e32 v0, v0
	v_cmp_lt_f32_e32 vcc, s23, v47
	s_nop 0
	s_nop 0
	v_cndmask_b32_e32 v47, 0, v0, vcc
	v_cmp_lt_f32_e32 vcc, s23, v48
	v_sub_f32_e32 v0, v96, v107
	s_nop 0
	v_cndmask_b32_e32 v48, 0, v112, vcc
	s_nop 1
	v_sub_f32_e32 v109, v49, v107
	v_exp_f32_e32 v0, v0
	s_nop 0
	v_exp_f32_e32 v109, v109
	v_cmp_lt_f32_e32 vcc, s23, v49
	s_nop 1
	v_cndmask_b32_e32 v49, 0, v109, vcc
	v_cmp_lt_f32_e32 vcc, s23, v96
	s_nop 1
	v_cndmask_b32_e32 v96, 0, v0, vcc
	v_sub_f32_e32 v0, v106, v107
	s_nop 1
	v_sub_f32_e32 v109, v105, v107
	v_exp_f32_e32 v0, v0
	s_nop 0
	v_exp_f32_e32 v109, v109
	v_cmp_lt_f32_e32 vcc, s23, v105
	s_nop 1
	v_cndmask_b32_e32 v105, 0, v109, vcc
	v_cmp_lt_f32_e32 vcc, s23, v106
	s_nop 1
	v_cndmask_b32_e32 v106, 0, v0, vcc
	v_sub_f32_e32 v0, v45, v107
	s_nop 1
	v_sub_f32_e32 v109, v44, v107
	v_exp_f32_e32 v0, v0
	s_nop 0
	v_exp_f32_e32 v109, v109
	v_cmp_lt_f32_e32 vcc, s23, v44
	s_nop 1
	v_cndmask_b32_e32 v109, 0, v109, vcc
	v_cmp_lt_f32_e32 vcc, s23, v45
	s_nop 1
	v_cndmask_b32_e32 v112, 0, v0, vcc
	v_sub_f32_e32 v0, v108, v107
	s_nop 1
	v_sub_f32_e32 v44, v110, v107
	v_exp_f32_e32 v0, v0
	s_nop 0
	v_exp_f32_e32 v44, v44
	v_cmp_lt_f32_e32 vcc, s23, v110
	s_nop 1
	v_cndmask_b32_e32 v110, 0, v44, vcc
	v_cmp_lt_f32_e32 vcc, s23, v108
	s_nop 1
	v_cndmask_b32_e32 v108, 0, v0, vcc
	v_sub_f32_e32 v0, v43, v107
	s_nop 1
	v_sub_f32_e32 v44, v42, v107
	v_exp_f32_e32 v0, v0
	s_nop 0
	v_exp_f32_e32 v44, v44
	v_cmp_lt_f32_e32 vcc, s23, v42
	s_nop 0
	s_nop 0
	v_cndmask_b32_e32 v114, 0, v44, vcc
	v_cmp_lt_f32_e32 vcc, s23, v43
	s_nop 0
	s_nop 0
	v_cndmask_b32_e32 v115, 0, v0, vcc
	v_sub_f32_e32 v0, v104, v107
	s_nop 1
	v_sub_f32_e32 v42, v91, v107
	v_exp_f32_e32 v0, v0
	s_nop 0
	v_exp_f32_e32 v42, v42
	v_cmp_lt_f32_e32 vcc, s23, v91
	s_nop 1
	v_cndmask_b32_e32 v91, 0, v42, vcc
	v_cmp_lt_f32_e32 vcc, s23, v104
	s_nop 1
	v_cndmask_b32_e32 v104, 0, v0, vcc
	v_add_f32_e32 v0, v46, v48
	v_add_f32_e32 v0, v113, v0
	v_add_f32_e32 v0, v47, v0
	v_add_f32_e32 v0, v96, v0
	v_add_f32_e32 v0, v106, v0
	v_add_f32_e32 v0, v49, v0
	v_add_f32_e32 v0, v105, v0
	v_add_f32_e32 v0, v112, v0
	v_add_f32_e32 v0, v108, v0
	v_add_f32_e32 v0, v109, v0
	v_mov_b32_e32 v42, v111
	v_add_f32_e32 v0, v110, v0
	v_exp_f32_e32 v42, v42
	v_add_f32_e32 v0, v115, v0
	v_add_f32_e32 v0, v104, v0
	v_add_f32_e32 v111, v114, v0
	v_mov_b32_e32 v0, v42
	v_pk_mul_f32 v[32:33], v[32:33], v[0:1] op_sel_hi:[1,0]
	v_pk_mul_f32 v[30:31], v[30:31], v[0:1] op_sel_hi:[1,0]
	v_pk_mul_f32 v[28:29], v[28:29], v[0:1] op_sel_hi:[1,0]
	v_pk_mul_f32 v[26:27], v[26:27], v[0:1] op_sel_hi:[1,0]
	v_pk_mul_f32 v[24:25], v[24:25], v[0:1] op_sel_hi:[1,0]
	v_pk_mul_f32 v[22:23], v[22:23], v[0:1] op_sel_hi:[1,0]
	v_pk_mul_f32 v[20:21], v[20:21], v[0:1] op_sel_hi:[1,0]
	v_pk_mul_f32 v[18:19], v[18:19], v[0:1] op_sel_hi:[1,0]
	v_pk_mul_f32 v[16:17], v[16:17], v[0:1] op_sel_hi:[1,0]
	v_cvt_pk_bf16_f32 v45, v49, v105
	v_cvt_pk_bf16_f32 v44, v96, v106
	v_cvt_pk_bf16_f32 v43, v113, v47
	v_cvt_pk_bf16_f32 v42, v46, v48
	v_pk_mul_f32 v[14:15], v[14:15], v[0:1] op_sel_hi:[1,0]
	v_pk_mul_f32 v[12:13], v[12:13], v[0:1] op_sel_hi:[1,0]
	v_pk_mul_f32 v[10:11], v[10:11], v[0:1] op_sel_hi:[1,0]
	v_pk_mul_f32 v[8:9], v[8:9], v[0:1] op_sel_hi:[1,0]
	v_pk_mul_f32 v[6:7], v[6:7], v[0:1] op_sel_hi:[1,0]
	v_pk_mul_f32 v[4:5], v[4:5], v[0:1] op_sel_hi:[1,0]
	v_pk_mul_f32 v[2:3], v[2:3], v[0:1] op_sel_hi:[1,0]
	s_waitcnt lgkmcnt(2)
	v_mfma_f32_32x32x16_bf16 v[18:33], v[38:41], v[42:45], v[18:33]
	s_waitcnt lgkmcnt(0)
	v_mfma_f32_32x32x16_bf16 v[2:17], v[34:37], v[42:45], v[2:17]
	ds_read_b64_tr_b16 v[34:35], v124 offset:2048
	ds_read_b64_tr_b16 v[36:37], v124 offset:3072
	v_cvt_pk_bf16_f32 v41, v114, v91
	v_cvt_pk_bf16_f32 v40, v115, v104
	v_cvt_pk_bf16_f32 v39, v109, v110
	v_cvt_pk_bf16_f32 v38, v112, v108
	ds_read_b64_tr_b16 v[44:45], v124 offset:3136
	ds_read_b64_tr_b16 v[42:43], v124 offset:2112
	s_waitcnt lgkmcnt(2)
	v_mfma_f32_32x32x16_bf16 v[18:33], v[34:37], v[38:41], v[18:33]
	v_add_f32_e32 v34, v91, v111
	ds_bpermute_b32 v35, v184, v34
	s_waitcnt lgkmcnt(0)
	s_waitcnt lgkmcnt(0)
	v_add_f32_e32 v34, v34, v35
	v_mfma_f32_32x32x16_bf16 v[2:17], v[42:45], v[38:41], v[2:17]
	v_fmac_f32_e32 v34, v130, v0
	v_mov_b32_e32 v130, v34
	s_branch .LBB0_626
